# fix phase step 3 (U * (mix + bias) in place): bias and the eight U pieces of a column group requested at the top of the group and picked up after the MFMAs (was eight load-wait-store round trips per g
# speedup vs baseline: 1.0104x; 1.0100x over previous
; __device__ __forceinline__ float bflo(unsigned w) { return __uint_as_float(w << 16); }
; __device__ __forceinline__ float bfhi(unsigned w) { return __uint_as_float(w & 0xffff0000u); }
; __device__ __forceinline__ void phase_fix(KP kp, int l, unsigned char* shm) {
;     ...
;         const float bias = kp->b_s[(l * 4 + g) * 128 + t];
; #pragma unroll
;         for (int db = 0; db < 8; ++db) {
;           bf16_t* up = U + (size_t)r * 512 + g * 128 + db * 16 + kg * 4;
;           const u32x2 uw = *(const u32x2*)up;
;           u32x2 ow;
;           ow[0] = cvt_pk_bf16(bflo(uw[0]) * (acc[db][0] + bias), bfhi(uw[0]) * (acc[db][1] + bias));
;           ow[1] = cvt_pk_bf16(bflo(uw[1]) * (acc[db][2] + bias), bfhi(uw[1]) * (acc[db][3] + bias));
;           *(u32x2*)up = ow;
;         }
.LBB0_2821:
	s_or_b64 exec, exec, s[22:23]
	s_waitcnt vmcnt(0)
	v_lshl_add_u64 v[18:19], s[14:15], 0, v[56:57]
	v_add_co_u32_e32 v18, vcc, 0xc822000, v18
	v_mov_b32_e32 v16, v234
	s_nop 0
	v_addc_co_u32_e32 v19, vcc, 0, v19, vcc
	v_mov_b32_e32 v62, v216
	v_mov_b32_e32 v63, v217
	s_mov_b64 s[22:23], 0x200
	s_add_i32 s24, s24, 0x8800
	v_lshl_add_u64 v[58:59], v[58:59], 0, s[22:23]
	s_mov_b64 s[22:23], 0x8000
	v_lshl_add_u64 v[56:57], v[56:57], 0, s[18:19]
	s_cmp_lg_u32 s24, 0x22000
	v_lshl_add_u64 v[60:61], v[60:61], 0, s[22:23]
	v_add_f32_e32 v32, v16, v32
	v_add_f32_e32 v33, v16, v33
	v_add_f32_e32 v34, v16, v34
	v_add_f32_e32 v35, v16, v35
	v_lshlrev_b32_e32 v51, 16, v62
	v_and_b32_e32 v55, 0xffff0000, v62
	v_lshlrev_b32_e32 v62, 16, v63
	v_and_b32_e32 v63, 0xffff0000, v63
	v_mul_f32_e32 v32, v32, v51
	v_mul_f32_e32 v33, v33, v55
	v_mul_f32_e32 v34, v34, v62
	v_mul_f32_e32 v35, v35, v63
	v_cvt_pk_bf16_f32 v32, v32, v33
	v_cvt_pk_bf16_f32 v33, v34, v35
	v_mov_b32_e32 v34, v218
	v_mov_b32_e32 v35, v219
	v_add_f32_e32 v28, v28, v16
	v_add_f32_e32 v29, v29, v16
	v_add_f32_e32 v30, v30, v16
	v_add_f32_e32 v31, v31, v16
	global_store_dwordx2 v[18:19], v[32:33], off
	v_add_f32_e32 v24, v24, v16
	v_add_f32_e32 v25, v25, v16
	v_add_f32_e32 v26, v26, v16
	v_add_f32_e32 v27, v27, v16
	v_add_f32_e32 v20, v20, v16
	v_add_f32_e32 v21, v21, v16
	v_add_f32_e32 v22, v22, v16
	v_add_f32_e32 v23, v23, v16
	v_add_f32_e32 v12, v12, v16
	v_add_f32_e32 v13, v13, v16
	v_add_f32_e32 v14, v14, v16
	v_add_f32_e32 v15, v15, v16
	v_add_f32_e32 v8, v8, v16
	v_add_f32_e32 v9, v9, v16
	v_add_f32_e32 v10, v10, v16
	v_add_f32_e32 v11, v11, v16
	v_add_f32_e32 v4, v4, v16
	v_add_f32_e32 v5, v5, v16
	v_add_f32_e32 v6, v6, v16
	v_add_f32_e32 v7, v7, v16
	v_add_f32_e32 v0, v0, v16
	v_add_f32_e32 v1, v1, v16
	v_add_f32_e32 v2, v2, v16
	v_add_f32_e32 v3, v3, v16
	v_lshlrev_b32_e32 v32, 16, v34
	v_and_b32_e32 v33, 0xffff0000, v34
	v_lshlrev_b32_e32 v34, 16, v35
	v_and_b32_e32 v35, 0xffff0000, v35
	v_mul_f32_e32 v28, v28, v32
	v_mul_f32_e32 v29, v29, v33
	v_mul_f32_e32 v30, v30, v34
	v_mul_f32_e32 v31, v31, v35
	v_cvt_pk_bf16_f32 v28, v28, v29
	v_cvt_pk_bf16_f32 v29, v30, v31
	v_mov_b32_e32 v30, v220
	v_mov_b32_e32 v31, v221
	s_nop 0
	global_store_dwordx2 v[18:19], v[28:29], off offset:32
	v_lshlrev_b32_e32 v28, 16, v30
	v_and_b32_e32 v29, 0xffff0000, v30
	v_lshlrev_b32_e32 v30, 16, v31
	v_and_b32_e32 v31, 0xffff0000, v31
	v_mul_f32_e32 v24, v24, v28
	v_mul_f32_e32 v25, v25, v29
	v_mul_f32_e32 v26, v26, v30
	v_mul_f32_e32 v27, v27, v31
	v_cvt_pk_bf16_f32 v24, v24, v25
	v_cvt_pk_bf16_f32 v25, v26, v27
	v_mov_b32_e32 v26, v222
	v_mov_b32_e32 v27, v223
	s_nop 0
	global_store_dwordx2 v[18:19], v[24:25], off offset:64
	v_lshlrev_b32_e32 v24, 16, v26
	v_and_b32_e32 v25, 0xffff0000, v26
	v_lshlrev_b32_e32 v26, 16, v27
	v_and_b32_e32 v27, 0xffff0000, v27
	v_mul_f32_e32 v20, v20, v24
	v_mul_f32_e32 v21, v21, v25
	v_mul_f32_e32 v22, v22, v26
	v_mul_f32_e32 v23, v23, v27
	v_cvt_pk_bf16_f32 v20, v20, v21
	v_cvt_pk_bf16_f32 v21, v22, v23
	v_mov_b32_e32 v22, v224
	v_mov_b32_e32 v23, v225
	s_nop 0
	global_store_dwordx2 v[18:19], v[20:21], off offset:96
	v_lshlrev_b32_e32 v20, 16, v22
	v_and_b32_e32 v21, 0xffff0000, v22
	v_lshlrev_b32_e32 v22, 16, v23
	v_and_b32_e32 v23, 0xffff0000, v23
	v_mul_f32_e32 v12, v12, v20
	v_mul_f32_e32 v13, v13, v21
	v_mul_f32_e32 v14, v14, v22
	v_mul_f32_e32 v15, v15, v23
	v_cvt_pk_bf16_f32 v12, v12, v13
	v_cvt_pk_bf16_f32 v13, v14, v15
	v_mov_b32_e32 v14, v226
	v_mov_b32_e32 v15, v227
	s_nop 0
	global_store_dwordx2 v[18:19], v[12:13], off offset:128
	v_lshlrev_b32_e32 v12, 16, v14
	v_and_b32_e32 v13, 0xffff0000, v14
	v_lshlrev_b32_e32 v14, 16, v15
	v_and_b32_e32 v15, 0xffff0000, v15
	v_mul_f32_e32 v8, v8, v12
	v_mul_f32_e32 v9, v9, v13
	v_mul_f32_e32 v10, v10, v14
	v_mul_f32_e32 v11, v11, v15
	v_cvt_pk_bf16_f32 v8, v8, v9
	v_cvt_pk_bf16_f32 v9, v10, v11
	v_mov_b32_e32 v10, v228
	v_mov_b32_e32 v11, v229
	s_nop 0
	global_store_dwordx2 v[18:19], v[8:9], off offset:160
	v_lshlrev_b32_e32 v8, 16, v10
	v_and_b32_e32 v9, 0xffff0000, v10
	v_lshlrev_b32_e32 v10, 16, v11
	v_and_b32_e32 v11, 0xffff0000, v11
	v_mul_f32_e32 v4, v4, v8
	v_mul_f32_e32 v5, v5, v9
	v_mul_f32_e32 v6, v6, v10
	v_mul_f32_e32 v7, v7, v11
	v_cvt_pk_bf16_f32 v4, v4, v5
	v_cvt_pk_bf16_f32 v5, v6, v7
	v_mov_b32_e32 v6, v230
	v_mov_b32_e32 v7, v231
	s_nop 0
	global_store_dwordx2 v[18:19], v[4:5], off offset:192
	v_lshlrev_b32_e32 v4, 16, v6
	v_and_b32_e32 v5, 0xffff0000, v6
	v_lshlrev_b32_e32 v6, 16, v7
	v_and_b32_e32 v7, 0xffff0000, v7
	v_mul_f32_e32 v0, v0, v4
	v_mul_f32_e32 v1, v1, v5
	v_mul_f32_e32 v2, v2, v6
	v_mul_f32_e32 v3, v3, v7
	v_cvt_pk_bf16_f32 v0, v0, v1
	v_cvt_pk_bf16_f32 v1, v2, v3
	global_store_dwordx2 v[18:19], v[0:1], off offset:224
	s_cbranch_scc0 .LBB0_2809
; __device__ __forceinline__ void phase_fix(KP kp, int l, unsigned char* shm) {
;     ...
;       for (int g = 0; g < 4; ++g) {
;         f32x4 acc[8];
; #pragma unroll
;         for (int db = 0; db < 8; ++db) acc[db] = (f32x4){0.f, 0.f, 0.f, 0.f};
; #pragma unroll
;         for (int ks = 0; ks < 4; ++ks) {
;           if (ks * 32 <= 16 * w + 15) {
;             const bf16x8 wf = *(const bf16x8*)(WSM + ((size_t)g * 128 + t) * 128 + ks * 32 + kg * 8);
; #pragma unroll
;             for (int db = 0; db < 8; ++db) {
;               const bf16x8 vf = *(const bf16x8*)(vnT + (size_t)(g * 128 + db * 16 + tl) * 136 + ks * 32 + kg * 8);
;               acc[db] = __builtin_amdgcn_mfma_f32_16x16x32_bf16(vf, wf, acc[db], 0, 0, 0);
;             }
;           }
;         }
;         const float bias = kp->b_s[(l * 4 + g) * 128 + t];
; #pragma unroll
;         for (int db = 0; db < 8; ++db) {
;           bf16_t* up = U + (size_t)r * 512 + g * 128 + db * 16 + kg * 4;
;           const u32x2 uw = *(const u32x2*)up;
.LBB0_2822:
	v_mov_b32_e32 v16, v17
	v_mov_b32_e32 v18, v17
	v_mov_b32_e32 v19, v17
	v_mov_b64_e32 v[0:1], v[16:17]
	v_mov_b64_e32 v[4:5], v[16:17]
	v_mov_b64_e32 v[8:9], v[16:17]
	v_mov_b64_e32 v[12:13], v[16:17]
	v_mov_b64_e32 v[22:23], v[18:19]
	v_mov_b64_e32 v[26:27], v[18:19]
	v_mov_b64_e32 v[30:31], v[18:19]
	v_mov_b64_e32 v[34:35], v[18:19]
	v_lshl_add_u64 v[62:63], s[14:15], 0, v[60:61]
	global_load_dwordx4 v[200:203], v[62:63], off offset:-128
	global_load_dwordx4 v[204:207], v[62:63], off offset:-64
	global_load_dwordx4 v[208:211], v[62:63], off
	global_load_dwordx4 v[212:215], v[62:63], off offset:64
	v_lshl_add_u64 v[232:233], s[14:15], 0, v[56:57]
	v_add_co_u32_e32 v232, vcc, 0xc822000, v232
	s_nop 1
	v_addc_co_u32_e32 v233, vcc, 0, v233, vcc
	global_load_dword v234, v[58:59], off
	global_load_dwordx2 v[216:217], v[232:233], off
	global_load_dwordx2 v[218:219], v[232:233], off offset:32
	global_load_dwordx2 v[220:221], v[232:233], off offset:64
	global_load_dwordx2 v[222:223], v[232:233], off offset:96
	global_load_dwordx2 v[224:225], v[232:233], off offset:128
	global_load_dwordx2 v[226:227], v[232:233], off offset:160
	global_load_dwordx2 v[228:229], v[232:233], off offset:192
	global_load_dwordx2 v[230:231], v[232:233], off offset:224
	v_add_u32_e32 v51, s24, v43
	v_mov_b64_e32 v[2:3], v[18:19]
	v_mov_b64_e32 v[6:7], v[18:19]
	v_mov_b64_e32 v[10:11], v[18:19]
	v_mov_b64_e32 v[14:15], v[18:19]
	v_mov_b64_e32 v[20:21], v[16:17]
	v_mov_b64_e32 v[24:25], v[16:17]
	v_mov_b64_e32 v[28:29], v[16:17]
	v_mov_b64_e32 v[32:33], v[16:17]
	s_and_saveexec_b64 s[22:23], s[2:3]
	s_cbranch_execz .Lfixmm_chk1
	ds_read_b128 v[96:99], v51
	ds_read_b128 v[100:103], v51 offset:4352
	ds_read_b128 v[104:107], v51 offset:8704
	ds_read_b128 v[108:111], v51 offset:13056
	ds_read_b128 v[112:115], v51 offset:17408
	ds_read_b128 v[116:119], v51 offset:21760
	ds_read_b128 v[120:123], v51 offset:26112
	ds_read_b128 v[124:127], v51 offset:30464
	s_waitcnt vmcnt(12)
	s_waitcnt lgkmcnt(7)
	v_mfma_f32_16x16x32_bf16 v[32:35], v[96:99], v[200:203], 0
	s_waitcnt lgkmcnt(6)
	v_mfma_f32_16x16x32_bf16 v[28:31], v[100:103], v[200:203], 0
	s_waitcnt lgkmcnt(5)
	v_mfma_f32_16x16x32_bf16 v[24:27], v[104:107], v[200:203], 0
	s_waitcnt lgkmcnt(4)
	v_mfma_f32_16x16x32_bf16 v[20:23], v[108:111], v[200:203], 0
	s_waitcnt lgkmcnt(3)
	v_mfma_f32_16x16x32_bf16 v[12:15], v[112:115], v[200:203], 0
	s_waitcnt lgkmcnt(2)
	v_mfma_f32_16x16x32_bf16 v[8:11], v[116:119], v[200:203], 0
	s_waitcnt lgkmcnt(1)
	v_mfma_f32_16x16x32_bf16 v[4:7], v[120:123], v[200:203], 0
	s_waitcnt lgkmcnt(0)
	v_mfma_f32_16x16x32_bf16 v[0:3], v[124:127], v[200:203], 0
.Lfixmm_chk1:
	s_or_b64 exec, exec, s[22:23]
	s_and_saveexec_b64 s[22:23], s[4:5]
	s_cbranch_execz .Lfixmm_chk2
	ds_read_b128 v[96:99], v51 offset:64
	ds_read_b128 v[100:103], v51 offset:4416
	ds_read_b128 v[104:107], v51 offset:8768
	ds_read_b128 v[108:111], v51 offset:13120
	ds_read_b128 v[112:115], v51 offset:17472
	ds_read_b128 v[116:119], v51 offset:21824
	ds_read_b128 v[120:123], v51 offset:26176
	ds_read_b128 v[124:127], v51 offset:30528
	s_waitcnt vmcnt(11)
	s_waitcnt lgkmcnt(7)
	v_mfma_f32_16x16x32_bf16 v[32:35], v[96:99], v[204:207], v[32:35]
	s_waitcnt lgkmcnt(6)
	v_mfma_f32_16x16x32_bf16 v[28:31], v[100:103], v[204:207], v[28:31]
	s_waitcnt lgkmcnt(5)
	v_mfma_f32_16x16x32_bf16 v[24:27], v[104:107], v[204:207], v[24:27]
	s_waitcnt lgkmcnt(4)
	v_mfma_f32_16x16x32_bf16 v[20:23], v[108:111], v[204:207], v[20:23]
	s_waitcnt lgkmcnt(3)
	v_mfma_f32_16x16x32_bf16 v[12:15], v[112:115], v[204:207], v[12:15]
	s_waitcnt lgkmcnt(2)
	v_mfma_f32_16x16x32_bf16 v[8:11], v[116:119], v[204:207], v[8:11]
	s_waitcnt lgkmcnt(1)
	v_mfma_f32_16x16x32_bf16 v[4:7], v[120:123], v[204:207], v[4:7]
	s_waitcnt lgkmcnt(0)
	v_mfma_f32_16x16x32_bf16 v[0:3], v[124:127], v[204:207], v[0:3]
.Lfixmm_chk2:
	s_or_b64 exec, exec, s[22:23]
	s_and_saveexec_b64 s[22:23], s[6:7]
	s_cbranch_execz .Lfixmm_chk3
	ds_read_b128 v[96:99], v51 offset:128
	ds_read_b128 v[100:103], v51 offset:4480
	ds_read_b128 v[104:107], v51 offset:8832
	ds_read_b128 v[108:111], v51 offset:13184
	ds_read_b128 v[112:115], v51 offset:17536
	ds_read_b128 v[116:119], v51 offset:21888
	ds_read_b128 v[120:123], v51 offset:26240
	ds_read_b128 v[124:127], v51 offset:30592
	s_waitcnt vmcnt(10)
	s_waitcnt lgkmcnt(7)
	v_mfma_f32_16x16x32_bf16 v[32:35], v[96:99], v[208:211], v[32:35]
	s_waitcnt lgkmcnt(6)
	v_mfma_f32_16x16x32_bf16 v[28:31], v[100:103], v[208:211], v[28:31]
	s_waitcnt lgkmcnt(5)
	v_mfma_f32_16x16x32_bf16 v[24:27], v[104:107], v[208:211], v[24:27]
	s_waitcnt lgkmcnt(4)
	v_mfma_f32_16x16x32_bf16 v[20:23], v[108:111], v[208:211], v[20:23]
	s_waitcnt lgkmcnt(3)
	v_mfma_f32_16x16x32_bf16 v[12:15], v[112:115], v[208:211], v[12:15]
	s_waitcnt lgkmcnt(2)
	v_mfma_f32_16x16x32_bf16 v[8:11], v[116:119], v[208:211], v[8:11]
	s_waitcnt lgkmcnt(1)
	v_mfma_f32_16x16x32_bf16 v[4:7], v[120:123], v[208:211], v[4:7]
	s_waitcnt lgkmcnt(0)
	v_mfma_f32_16x16x32_bf16 v[0:3], v[124:127], v[208:211], v[0:3]
.Lfixmm_chk3:
	s_or_b64 exec, exec, s[22:23]
	s_and_saveexec_b64 s[22:23], s[8:9]
	s_cbranch_execz .LBB0_2821
	ds_read_b128 v[96:99], v51 offset:192
	ds_read_b128 v[100:103], v51 offset:4544
	ds_read_b128 v[104:107], v51 offset:8896
	ds_read_b128 v[108:111], v51 offset:13248
	ds_read_b128 v[112:115], v51 offset:17600
	ds_read_b128 v[116:119], v51 offset:21952
	ds_read_b128 v[120:123], v51 offset:26304
	ds_read_b128 v[124:127], v51 offset:30656
	s_waitcnt vmcnt(9)
	s_waitcnt lgkmcnt(7)
	v_mfma_f32_16x16x32_bf16 v[32:35], v[96:99], v[212:215], v[32:35]
	s_waitcnt lgkmcnt(6)
	v_mfma_f32_16x16x32_bf16 v[28:31], v[100:103], v[212:215], v[28:31]
	s_waitcnt lgkmcnt(5)
	v_mfma_f32_16x16x32_bf16 v[24:27], v[104:107], v[212:215], v[24:27]
	s_waitcnt lgkmcnt(4)
	v_mfma_f32_16x16x32_bf16 v[20:23], v[108:111], v[212:215], v[20:23]
	s_waitcnt lgkmcnt(3)
	v_mfma_f32_16x16x32_bf16 v[12:15], v[112:115], v[212:215], v[12:15]
	s_waitcnt lgkmcnt(2)
	v_mfma_f32_16x16x32_bf16 v[8:11], v[116:119], v[212:215], v[8:11]
	s_waitcnt lgkmcnt(1)
	v_mfma_f32_16x16x32_bf16 v[4:7], v[120:123], v[212:215], v[4:7]
	s_waitcnt lgkmcnt(0)
	v_mfma_f32_16x16x32_bf16 v[0:3], v[124:127], v[212:215], v[0:3]
	s_branch .LBB0_2821
